# NSA selected branch: two K/V tiles of global loads in flight (second register staging set, loop unrolled by buffer parity) on top of the 16x16x32 group-skipping step
# speedup vs baseline: 1.0228x; 1.0117x over previous
.LBB0_2164:
	s_or_b64 exec, exec, s[20:21]
	v_add_u32_e32 v38, v34, v35
	v_bcnt_u32_b32 v37, v37, 0
	v_add_u32_e32 v38, v38, v36
	v_add_u32_e32 v150, v38, v37
	v_mul_f32_e32 v38, v133, v146
	v_cmp_eq_u32_e32 vcc, 0, v150
	v_pk_mul_f32 v[82:83], v[38:39], v[18:19] op_sel_hi:[0,1]
	v_add_u32_e32 v215, 0x9000, v214
	v_pk_mul_f32 v[84:85], v[38:39], v[20:21] op_sel_hi:[0,1]
	v_add_u32_e32 v216, 0x9008, v214
	v_pk_mul_f32 v[86:87], v[38:39], v[22:23] op_sel_hi:[0,1]
	v_add_u32_e32 v217, 0x9020, v214
	v_pk_mul_f32 v[88:89], v[38:39], v[24:25] op_sel_hi:[0,1]
	v_add_u32_e32 v218, 0x9028, v214
	v_pk_mul_f32 v[90:91], v[38:39], v[26:27] op_sel_hi:[0,1]
	v_add_u32_e32 v219, 0x9040, v214
	v_pk_mul_f32 v[92:93], v[38:39], v[28:29] op_sel_hi:[0,1]
	v_add_u32_e32 v220, 0x9048, v214
	v_pk_mul_f32 v[94:95], v[38:39], v[30:31] op_sel_hi:[0,1]
	v_add_u32_e32 v221, 0x9060, v214
	v_pk_mul_f32 v[96:97], v[38:39], v[32:33] op_sel_hi:[0,1]
	v_add_u32_e32 v222, 0x9068, v214
	v_pk_mul_f32 v[134:135], v[38:39], v[2:3] op_sel_hi:[0,1]
	v_add_u32_e32 v223, 0x9080, v214
	v_pk_mul_f32 v[136:137], v[38:39], v[4:5] op_sel_hi:[0,1]
	v_add_u32_e32 v224, 0x9088, v214
	v_pk_mul_f32 v[138:139], v[38:39], v[6:7] op_sel_hi:[0,1]
	v_add_u32_e32 v225, 0x90a0, v214
	v_pk_mul_f32 v[140:141], v[38:39], v[8:9] op_sel_hi:[0,1]
	v_add_u32_e32 v226, 0x90a8, v214
	v_pk_mul_f32 v[142:143], v[38:39], v[10:11] op_sel_hi:[0,1]
	v_add_u32_e32 v227, 0x90c0, v214
	v_pk_mul_f32 v[144:145], v[38:39], v[12:13] op_sel_hi:[0,1]
	v_add_u32_e32 v228, 0x90c8, v214
	v_pk_mul_f32 v[146:147], v[38:39], v[14:15] op_sel_hi:[0,1]
	v_add_u32_e32 v229, 0x90e0, v214
	v_pk_mul_f32 v[148:149], v[38:39], v[16:17] op_sel_hi:[0,1]
	v_add_u32_e32 v230, 0x90e8, v214
	s_and_b64 vcc, exec, vcc
	s_lshl_b32 s24, s71, 19
	s_waitcnt lgkmcnt(0)
	s_barrier
	ds_write2_b32 v215, v82, v83 offset1:1
	ds_write2_b32 v216, v84, v85 offset1:1
	ds_write2_b32 v217, v86, v87 offset1:1
	ds_write2_b32 v218, v88, v89 offset1:1
	ds_write2_b32 v219, v90, v91 offset1:1
	ds_write2_b32 v220, v92, v93 offset1:1
	ds_write2_b32 v221, v94, v95 offset1:1
	ds_write2_b32 v222, v96, v97 offset1:1
	ds_write2_b32 v223, v134, v135 offset1:1
	ds_write2_b32 v224, v136, v137 offset1:1
	ds_write2_b32 v225, v138, v139 offset1:1
	ds_write2_b32 v226, v140, v141 offset1:1
	ds_write2_b32 v227, v142, v143 offset1:1
	ds_write2_b32 v228, v144, v145 offset1:1
	ds_write2_b32 v229, v146, v147 offset1:1
	ds_write2_b32 v230, v148, v149 offset1:1
	s_cbranch_vccnz .LBB0_2181
	s_lshl_b32 s96, s66, 12
	s_and_b32 s96, s96, 0x6000
	s_lshl_b32 s95, s66, 3
	s_and_b32 s95, s95, 8
	s_sub_i32 s94, 0x1ff0, s70
	s_mov_b32 s86, 0xff00ff00
	s_mov_b32 s87, 0xff00ff00
	s_mov_b32 s98, 0x1000
	s_mov_b32 s99, 0
	v_and_b32_e32 v40, 15, v166
	v_bfe_u32 v41, v166, 4, 2
	v_lshrrev_b32_e32 v42, 6, v166
	v_mul_u32_u24_e32 v234, 0x90, v40
	v_lshl_add_u32 v234, v41, 4, v234
	v_bfe_u32 v43, v166, 3, 1
	v_lshl_add_u32 v43, v42, 2, v43
	v_add_u32_e32 v236, s94, v43
	v_lshlrev_b32_e32 v44, 2, v41
	v_sub_u32_e32 v239, v236, v44
	v_lshl_add_u32 v45, v42, 5, v40
	v_mul_u32_u24_e32 v45, 0x41, v45
	v_lshl_add_u32 v45, v41, 2, v45
	v_lshlrev_b32_e32 v45, 2, v45
	v_add_u32_e32 v237, 0x9000, v45
	v_add_u32_e32 v238, 0x1040, v237
	v_add_u32_e32 v46, s96, v236
	v_mov_b32_e32 v47, 0
	v_lshlrev_b64 v[46:47], 11, v[46:47]
	v_lshl_add_u64 v[46:47], s[42:43], 0, v[46:47]
	v_and_b32_e32 v48, 7, v166
	v_or_b32_e32 v48, s95, v48
	v_lshlrev_b32_e32 v48, 7, v48
	v_lshl_add_u32 v48, v41, 4, v48
	v_mov_b32_e32 v49, 0
	v_lshl_add_u64 v[46:47], v[46:47], 0, v[48:49]
	global_load_dwordx4 v[66:69], v[46:47], off
	global_load_dwordx4 v[70:73], v[46:47], off offset:64
	v_lshl_add_u64 v[48:49], v[46:47], 0, s[98:99]
	global_load_dwordx4 v[74:77], v[48:49], off
	global_load_dwordx4 v[78:81], v[48:49], off offset:64
	v_mov_b32_e32 v235, 0
	s_lshl_b32 s22, s24, 1
	v_readlane_b32 s20, v231, 14
	s_add_u32 s20, s20, s22
	v_readlane_b32 s21, v231, 10
	s_addc_u32 s21, s21, 0
	s_add_u32 s22, s52, s22
	s_addc_u32 s23, s53, 0
	v_mov_b32_e32 v129, v105
	v_lshl_add_u64 v[134:135], s[20:21], 0, v[128:129]
	v_lshl_add_u64 v[136:137], s[22:23], 0, v[128:129]
	v_readfirstlane_b32 s101, v150
	s_mov_b32 s25, 0x11300
	s_mov_b32 s20, 0
	v_mov_b32_e32 v34, s25
	ds_read_b32 v34, v34
	s_waitcnt lgkmcnt(0)
	v_ashrrev_i32_e32 v35, 31, v34
	v_lshlrev_b64 v[34:35], 13, v[34:35]
	v_lshl_add_u64 v[36:37], v[134:135], 0, v[34:35]
	v_lshl_add_u64 v[34:35], v[136:137], 0, v[34:35]
	v_lshl_add_u64 v[38:39], v[36:37], 0, v[106:107]
	v_lshl_add_u64 v[36:37], v[36:37], 0, v[108:109]
	v_lshl_add_u64 v[40:41], v[34:35], 0, v[106:107]
	global_load_dwordx4 v[82:85], v[38:39], off
	global_load_dwordx4 v[86:89], v[40:41], off
	v_lshl_add_u64 v[34:35], v[34:35], 0, v[108:109]
	global_load_dwordx4 v[90:93], v[36:37], off
	global_load_dwordx4 v[94:97], v[34:35], off
	s_cmp_lt_u32 s101, 2
	s_cbranch_scc1 .Lsb16_pa
	v_mov_b32_e32 v34, s25
	ds_read_b32 v34, v34 offset:4
	s_waitcnt lgkmcnt(0)
	v_ashrrev_i32_e32 v35, 31, v34
	v_lshlrev_b64 v[34:35], 13, v[34:35]
	v_lshl_add_u64 v[36:37], v[134:135], 0, v[34:35]
	v_lshl_add_u64 v[34:35], v[136:137], 0, v[34:35]
	v_lshl_add_u64 v[38:39], v[36:37], 0, v[106:107]
	v_lshl_add_u64 v[36:37], v[36:37], 0, v[108:109]
	v_lshl_add_u64 v[40:41], v[34:35], 0, v[106:107]
	global_load_dwordx4 v[240:243], v[38:39], off
	global_load_dwordx4 v[244:247], v[40:41], off
	v_lshl_add_u64 v[34:35], v[34:35], 0, v[108:109]
	global_load_dwordx4 v[248:251], v[36:37], off
	global_load_dwordx4 v[252:255], v[34:35], off
	s_waitcnt vmcnt(4)
	s_branch .Lsb16_pb

.Lsb16_pb:
	ds_write_b128 v153, v[82:85]
	ds_write_b128 v153, v[86:89] offset:9216
	ds_write_b128 v155, v[90:93]
	ds_write_b128 v155, v[94:97] offset:9216
	s_cmp_lt_u32 s101, 3
	s_cbranch_scc1 .Lsb16_pc
	v_mov_b32_e32 v34, s25
	ds_read_b32 v34, v34 offset:8
	s_waitcnt lgkmcnt(0)
	v_ashrrev_i32_e32 v35, 31, v34
	v_lshlrev_b64 v[34:35], 13, v[34:35]
	v_lshl_add_u64 v[36:37], v[134:135], 0, v[34:35]
	v_lshl_add_u64 v[34:35], v[136:137], 0, v[34:35]
	v_lshl_add_u64 v[38:39], v[36:37], 0, v[106:107]
	v_lshl_add_u64 v[36:37], v[36:37], 0, v[108:109]
	v_lshl_add_u64 v[40:41], v[34:35], 0, v[106:107]
	global_load_dwordx4 v[82:85], v[38:39], off
	global_load_dwordx4 v[86:89], v[40:41], off
	v_lshl_add_u64 v[34:35], v[34:35], 0, v[108:109]
	global_load_dwordx4 v[90:93], v[36:37], off
	global_load_dwordx4 v[94:97], v[34:35], off
.Lsb16_pc:
	v_mov_b32_e32 v2, 0
	v_mov_b32_e32 v3, 0
	v_mov_b32_e32 v4, 0
	v_mov_b32_e32 v5, 0
	v_mov_b32_e32 v6, 0
	v_mov_b32_e32 v7, 0
	v_mov_b32_e32 v8, 0
	v_mov_b32_e32 v9, 0
	v_mov_b32_e32 v10, 0
	v_mov_b32_e32 v11, 0
	v_mov_b32_e32 v12, 0
	v_mov_b32_e32 v13, 0
	v_mov_b32_e32 v14, 0
	v_mov_b32_e32 v15, 0
	v_mov_b32_e32 v16, 0
	v_mov_b32_e32 v17, 0
	v_mov_b32_e32 v18, 0
	v_mov_b32_e32 v19, 0
	v_mov_b32_e32 v20, 0
	v_mov_b32_e32 v21, 0
	v_mov_b32_e32 v22, 0
	v_mov_b32_e32 v23, 0
	v_mov_b32_e32 v24, 0
	v_mov_b32_e32 v25, 0
	v_mov_b32_e32 v26, 0
	v_mov_b32_e32 v27, 0
	v_mov_b32_e32 v28, 0
	v_mov_b32_e32 v29, 0
	v_mov_b32_e32 v30, 0
	v_mov_b32_e32 v31, 0
	v_mov_b32_e32 v32, 0
	v_mov_b32_e32 v33, 0
	v_mov_b32_e32 v129, 0
	s_waitcnt lgkmcnt(0)
	s_barrier
.Lsb16_step_0:
	s_add_i32 s28, s20, 1
	s_cmp_ge_u32 s28, s101
	s_cbranch_scc1 .Lsb16_nost_0
	s_add_i32 s22, s20, 2
	s_cmp_ge_u32 s22, s101
	s_cbranch_scc1 .Lsb16_w0_0
	s_waitcnt vmcnt(4)
	s_branch .Lsb16_wr_0

.Lsb16_wr_0:
	ds_write_b128 v153, v[240:243] offset:18432
	ds_write_b128 v153, v[244:247] offset:27648
	ds_write_b128 v155, v[248:251] offset:18432
	ds_write_b128 v155, v[252:255] offset:27648
	s_add_i32 s22, s20, 3
	s_cmp_ge_u32 s22, s101
	s_cbranch_scc1 .Lsb16_nost_0
	v_mov_b32_e32 v34, s25
	ds_read_b32 v34, v34 offset:12
	s_waitcnt lgkmcnt(0)
	v_ashrrev_i32_e32 v35, 31, v34
	v_lshlrev_b64 v[34:35], 13, v[34:35]
	v_lshl_add_u64 v[36:37], v[134:135], 0, v[34:35]
	v_lshl_add_u64 v[34:35], v[136:137], 0, v[34:35]
	v_lshl_add_u64 v[38:39], v[36:37], 0, v[106:107]
	v_lshl_add_u64 v[36:37], v[36:37], 0, v[108:109]
	v_lshl_add_u64 v[40:41], v[34:35], 0, v[106:107]
	global_load_dwordx4 v[240:243], v[38:39], off
	global_load_dwordx4 v[244:247], v[40:41], off
	v_lshl_add_u64 v[34:35], v[34:35], 0, v[108:109]
	global_load_dwordx4 v[248:251], v[36:37], off
	global_load_dwordx4 v[252:255], v[34:35], off
.Lsb16_nost_0:
	v_mov_b32_e32 v34, s25
	ds_read_b32 v138, v34
	s_waitcnt lgkmcnt(0)
	v_readfirstlane_b32 s76, v138
	s_lshr_b32 s77, s76, 5
	s_lshl_b32 s77, s77, 2
	s_and_b32 s78, s76, 31
	v_add_u32_e32 v35, s77, v168
	v_add_u32_e32 v35, 0x11200, v35
	ds_read2_b32 v[36:37], v35 offset1:4
	ds_read2_b32 v[38:39], v35 offset0:8 offset1:12
	s_waitcnt lgkmcnt(0)
	v_or_b32_e32 v34, v36, v37
	v_or_b32_e32 v35, v38, v39
	s_nop 0
	v_readfirstlane_b32 s79, v34
	v_readfirstlane_b32 s80, v35
	s_bitcmp1_b32 s79, s78
	s_cselect_b32 s81, 1, 0
	s_bitcmp1_b32 s80, s78
	s_cselect_b32 s82, 1, 0
	s_or_b32 s83, s81, s82
	s_cmp_eq_u32 s83, 0
	s_cbranch_scc1 .Lsb16_end_0
	s_lshl_b32 s83, s76, 6
	v_subrev_u32_e32 v147, s83, v239
	v_cndmask_b32_e64 v146, v36, v37, s[86:87]
	v_cndmask_b32_e64 v151, v38, v39, s[86:87]
	v_lshrrev_b32_e32 v146, s78, v146
	v_lshrrev_b32_e32 v151, s78, v151
	v_and_b32_e32 v146, 1, v146
	v_and_b32_e32 v151, 1, v151
	v_cmp_ne_u32_e32 vcc, 0, v146
	s_cmp_eq_u32 s81, 0
	s_nop 0
	v_cndmask_b32_e32 v146, v213, v100, vcc
	s_cbranch_scc1 .Lsb16_g1_0
	ds_read_b128 v[50:53], v234
	ds_read_b128 v[54:57], v234 offset:64
	ds_read_b128 v[58:61], v234 offset:2304
	ds_read_b128 v[62:65], v234 offset:2368
	s_waitcnt lgkmcnt(3)
	v_mfma_f32_16x16x32_bf16 v[34:37], v[50:53], v[66:69], 0
	s_waitcnt lgkmcnt(2)
	v_mfma_f32_16x16x32_bf16 v[34:37], v[54:57], v[70:73], v[34:37]
	ds_read_b128 v[50:53], v234 offset:4608
	ds_read_b128 v[54:57], v234 offset:4672
	s_waitcnt lgkmcnt(3)
	v_mfma_f32_16x16x32_bf16 v[38:41], v[58:61], v[66:69], 0
	s_waitcnt lgkmcnt(2)
	v_mfma_f32_16x16x32_bf16 v[38:41], v[62:65], v[70:73], v[38:41]
	ds_read_b128 v[58:61], v234 offset:6912
	ds_read_b128 v[62:65], v234 offset:6976
	s_waitcnt lgkmcnt(3)
	v_mfma_f32_16x16x32_bf16 v[42:45], v[50:53], v[66:69], 0
	s_waitcnt lgkmcnt(2)
	v_mfma_f32_16x16x32_bf16 v[42:45], v[54:57], v[70:73], v[42:45]
	s_waitcnt lgkmcnt(1)
	v_mfma_f32_16x16x32_bf16 v[46:49], v[58:61], v[66:69], 0
	s_waitcnt lgkmcnt(0)
	v_mfma_f32_16x16x32_bf16 v[46:49], v[62:65], v[70:73], v[46:49]
	ds_read_b128 v[50:53], v234 offset:9216
	ds_read_b128 v[54:57], v234 offset:9280
	ds_read_b128 v[58:61], v234 offset:11520
	ds_read_b128 v[62:65], v234 offset:11584
	v_pk_fma_f32 v[34:35], v[34:35], s[48:49], v[146:147] op_sel_hi:[1,0,0]
	v_pk_fma_f32 v[36:37], v[36:37], s[48:49], v[146:147] op_sel_hi:[1,0,0]
	v_pk_fma_f32 v[38:39], v[38:39], s[48:49], v[146:147] op_sel_hi:[1,0,0]
	v_pk_fma_f32 v[40:41], v[40:41], s[48:49], v[146:147] op_sel_hi:[1,0,0]
	v_pk_fma_f32 v[42:43], v[42:43], s[48:49], v[146:147] op_sel_hi:[1,0,0]
	v_pk_fma_f32 v[44:45], v[44:45], s[48:49], v[146:147] op_sel_hi:[1,0,0]
	v_pk_fma_f32 v[46:47], v[46:47], s[48:49], v[146:147] op_sel_hi:[1,0,0]
	v_pk_fma_f32 v[48:49], v[48:49], s[48:49], v[146:147] op_sel_hi:[1,0,0]
	s_cmp_lg_u32 s76, s72
	s_cbranch_scc1 .Lsb16_nm0_0
	v_cmp_le_i32_e64 s[98:99], 0, v147
	s_nop 1
	v_cndmask_b32_e64 v34, v213, v34, s[98:99]
	v_cmp_le_i32_e64 s[98:99], 1, v147
	s_nop 1
	v_cndmask_b32_e64 v35, v213, v35, s[98:99]
	v_cmp_le_i32_e64 s[98:99], 2, v147
	s_nop 1
	v_cndmask_b32_e64 v36, v213, v36, s[98:99]
	v_cmp_le_i32_e64 s[98:99], 3, v147
	s_nop 1
	v_cndmask_b32_e64 v37, v213, v37, s[98:99]
	v_cmp_le_i32_e64 s[98:99], 16, v147
	s_nop 1
	v_cndmask_b32_e64 v38, v213, v38, s[98:99]
	v_cmp_le_i32_e64 s[98:99], 17, v147
	s_nop 1
	v_cndmask_b32_e64 v39, v213, v39, s[98:99]
	v_cmp_le_i32_e64 s[98:99], 18, v147
	s_nop 1
	v_cndmask_b32_e64 v40, v213, v40, s[98:99]
	v_cmp_le_i32_e64 s[98:99], 19, v147
	s_nop 1
	v_cndmask_b32_e64 v41, v213, v41, s[98:99]
	v_cmp_le_i32_e64 s[98:99], 32, v147
	s_nop 1
	v_cndmask_b32_e64 v42, v213, v42, s[98:99]
	v_cmp_le_i32_e64 s[98:99], 33, v147
	s_nop 1
	v_cndmask_b32_e64 v43, v213, v43, s[98:99]
	v_cmp_le_i32_e64 s[98:99], 34, v147
	s_nop 1
	v_cndmask_b32_e64 v44, v213, v44, s[98:99]
	v_cmp_le_i32_e64 s[98:99], 35, v147
	s_nop 1
	v_cndmask_b32_e64 v45, v213, v45, s[98:99]
	v_cmp_le_i32_e64 s[98:99], 48, v147
	s_nop 1
	v_cndmask_b32_e64 v46, v213, v46, s[98:99]
	v_cmp_le_i32_e64 s[98:99], 49, v147
	s_nop 1
	v_cndmask_b32_e64 v47, v213, v47, s[98:99]
	v_cmp_le_i32_e64 s[98:99], 50, v147
	s_nop 1
	v_cndmask_b32_e64 v48, v213, v48, s[98:99]
	v_cmp_le_i32_e64 s[98:99], 51, v147
	s_nop 1
	v_cndmask_b32_e64 v49, v213, v49, s[98:99]
.Lsb16_nm0_0:
	v_exp_f32_e32 v34, v34
	v_exp_f32_e32 v35, v35
	v_exp_f32_e32 v36, v36
	v_exp_f32_e32 v37, v37
	v_exp_f32_e32 v38, v38
	v_exp_f32_e32 v39, v39
	v_exp_f32_e32 v40, v40
	v_exp_f32_e32 v41, v41
	v_exp_f32_e32 v42, v42
	v_exp_f32_e32 v43, v43
	v_exp_f32_e32 v44, v44
	v_exp_f32_e32 v45, v45
	v_exp_f32_e32 v46, v46
	v_exp_f32_e32 v47, v47
	v_exp_f32_e32 v48, v48
	v_exp_f32_e32 v49, v49
	v_pk_add_f32 v[138:139], v[34:35], v[36:37]
	v_pk_add_f32 v[140:141], v[38:39], v[40:41]
	v_pk_add_f32 v[142:143], v[42:43], v[44:45]
	v_pk_add_f32 v[144:145], v[46:47], v[48:49]
	v_pk_add_f32 v[138:139], v[138:139], v[140:141]
	v_pk_add_f32 v[142:143], v[142:143], v[144:145]
	v_pk_add_f32 v[138:139], v[138:139], v[142:143]
	v_add_f32_e32 v140, v138, v139
	v_add_f32_e32 v129, v129, v140
	v_cvt_pk_bf16_f32 v138, v34, v35
	v_cvt_pk_bf16_f32 v139, v36, v37
	v_cvt_pk_bf16_f32 v140, v38, v39
	v_cvt_pk_bf16_f32 v141, v40, v41
	v_cvt_pk_bf16_f32 v142, v42, v43
	v_cvt_pk_bf16_f32 v143, v44, v45
	v_cvt_pk_bf16_f32 v144, v46, v47
	v_cvt_pk_bf16_f32 v145, v48, v49
	s_waitcnt lgkmcnt(3)
	v_mfma_f32_16x16x32_bf16 v[2:5], v[50:53], v[138:141], v[2:5]
	s_waitcnt lgkmcnt(2)
	v_mfma_f32_16x16x32_bf16 v[2:5], v[54:57], v[142:145], v[2:5]
	ds_read_b128 v[50:53], v234 offset:13824
	ds_read_b128 v[54:57], v234 offset:13888
	s_waitcnt lgkmcnt(3)
	v_mfma_f32_16x16x32_bf16 v[6:9], v[58:61], v[138:141], v[6:9]
	s_waitcnt lgkmcnt(2)
	v_mfma_f32_16x16x32_bf16 v[6:9], v[62:65], v[142:145], v[6:9]
	ds_read_b128 v[58:61], v234 offset:16128
	ds_read_b128 v[62:65], v234 offset:16192
	s_waitcnt lgkmcnt(3)
	v_mfma_f32_16x16x32_bf16 v[10:13], v[50:53], v[138:141], v[10:13]
	s_waitcnt lgkmcnt(2)
	v_mfma_f32_16x16x32_bf16 v[10:13], v[54:57], v[142:145], v[10:13]
	s_waitcnt lgkmcnt(1)
	v_mfma_f32_16x16x32_bf16 v[14:17], v[58:61], v[138:141], v[14:17]
	s_waitcnt lgkmcnt(0)
	v_mfma_f32_16x16x32_bf16 v[14:17], v[62:65], v[142:145], v[14:17]
.Lsb16_g1_0:
	s_cmp_eq_u32 s82, 0
	s_cbranch_scc1 .Lsb16_end_0
	v_cmp_ne_u32_e32 vcc, 0, v151
	v_add_u32_e32 v147, 2, v147
	ds_read_b128 v[50:53], v234
	ds_read_b128 v[54:57], v234 offset:64
	ds_read_b128 v[58:61], v234 offset:2304
	ds_read_b128 v[62:65], v234 offset:2368
	v_cndmask_b32_e32 v146, v213, v100, vcc
	s_waitcnt lgkmcnt(3)
	v_mfma_f32_16x16x32_bf16 v[34:37], v[50:53], v[74:77], 0
	s_waitcnt lgkmcnt(2)
	v_mfma_f32_16x16x32_bf16 v[34:37], v[54:57], v[78:81], v[34:37]
	ds_read_b128 v[50:53], v234 offset:4608
	ds_read_b128 v[54:57], v234 offset:4672
	s_waitcnt lgkmcnt(3)
	v_mfma_f32_16x16x32_bf16 v[38:41], v[58:61], v[74:77], 0
	s_waitcnt lgkmcnt(2)
	v_mfma_f32_16x16x32_bf16 v[38:41], v[62:65], v[78:81], v[38:41]
	ds_read_b128 v[58:61], v234 offset:6912
	ds_read_b128 v[62:65], v234 offset:6976
	s_waitcnt lgkmcnt(3)
	v_mfma_f32_16x16x32_bf16 v[42:45], v[50:53], v[74:77], 0
	s_waitcnt lgkmcnt(2)
	v_mfma_f32_16x16x32_bf16 v[42:45], v[54:57], v[78:81], v[42:45]
	s_waitcnt lgkmcnt(1)
	v_mfma_f32_16x16x32_bf16 v[46:49], v[58:61], v[74:77], 0
	s_waitcnt lgkmcnt(0)
	v_mfma_f32_16x16x32_bf16 v[46:49], v[62:65], v[78:81], v[46:49]
	ds_read_b128 v[50:53], v234 offset:9216
	ds_read_b128 v[54:57], v234 offset:9280
	ds_read_b128 v[58:61], v234 offset:11520
	ds_read_b128 v[62:65], v234 offset:11584
	v_pk_fma_f32 v[34:35], v[34:35], s[48:49], v[146:147] op_sel_hi:[1,0,0]
	v_pk_fma_f32 v[36:37], v[36:37], s[48:49], v[146:147] op_sel_hi:[1,0,0]
	v_pk_fma_f32 v[38:39], v[38:39], s[48:49], v[146:147] op_sel_hi:[1,0,0]
	v_pk_fma_f32 v[40:41], v[40:41], s[48:49], v[146:147] op_sel_hi:[1,0,0]
	v_pk_fma_f32 v[42:43], v[42:43], s[48:49], v[146:147] op_sel_hi:[1,0,0]
	v_pk_fma_f32 v[44:45], v[44:45], s[48:49], v[146:147] op_sel_hi:[1,0,0]
	v_pk_fma_f32 v[46:47], v[46:47], s[48:49], v[146:147] op_sel_hi:[1,0,0]
	v_pk_fma_f32 v[48:49], v[48:49], s[48:49], v[146:147] op_sel_hi:[1,0,0]
	s_cmp_lg_u32 s76, s72
	s_cbranch_scc1 .Lsb16_nm1_0
	v_cmp_le_i32_e64 s[98:99], 0, v147
	s_nop 1
	v_cndmask_b32_e64 v34, v213, v34, s[98:99]
	v_cmp_le_i32_e64 s[98:99], 1, v147
	s_nop 1
	v_cndmask_b32_e64 v35, v213, v35, s[98:99]
	v_cmp_le_i32_e64 s[98:99], 2, v147
	s_nop 1
	v_cndmask_b32_e64 v36, v213, v36, s[98:99]
	v_cmp_le_i32_e64 s[98:99], 3, v147
	s_nop 1
	v_cndmask_b32_e64 v37, v213, v37, s[98:99]
	v_cmp_le_i32_e64 s[98:99], 16, v147
	s_nop 1
	v_cndmask_b32_e64 v38, v213, v38, s[98:99]
	v_cmp_le_i32_e64 s[98:99], 17, v147
	s_nop 1
	v_cndmask_b32_e64 v39, v213, v39, s[98:99]
	v_cmp_le_i32_e64 s[98:99], 18, v147
	s_nop 1
	v_cndmask_b32_e64 v40, v213, v40, s[98:99]
	v_cmp_le_i32_e64 s[98:99], 19, v147
	s_nop 1
	v_cndmask_b32_e64 v41, v213, v41, s[98:99]
	v_cmp_le_i32_e64 s[98:99], 32, v147
	s_nop 1
	v_cndmask_b32_e64 v42, v213, v42, s[98:99]
	v_cmp_le_i32_e64 s[98:99], 33, v147
	s_nop 1
	v_cndmask_b32_e64 v43, v213, v43, s[98:99]
	v_cmp_le_i32_e64 s[98:99], 34, v147
	s_nop 1
	v_cndmask_b32_e64 v44, v213, v44, s[98:99]
	v_cmp_le_i32_e64 s[98:99], 35, v147
	s_nop 1
	v_cndmask_b32_e64 v45, v213, v45, s[98:99]
	v_cmp_le_i32_e64 s[98:99], 48, v147
	s_nop 1
	v_cndmask_b32_e64 v46, v213, v46, s[98:99]
	v_cmp_le_i32_e64 s[98:99], 49, v147
	s_nop 1
	v_cndmask_b32_e64 v47, v213, v47, s[98:99]
	v_cmp_le_i32_e64 s[98:99], 50, v147
	s_nop 1
	v_cndmask_b32_e64 v48, v213, v48, s[98:99]
	v_cmp_le_i32_e64 s[98:99], 51, v147
	s_nop 1
	v_cndmask_b32_e64 v49, v213, v49, s[98:99]
.Lsb16_nm1_0:
	v_exp_f32_e32 v34, v34
	v_exp_f32_e32 v35, v35
	v_exp_f32_e32 v36, v36
	v_exp_f32_e32 v37, v37
	v_exp_f32_e32 v38, v38
	v_exp_f32_e32 v39, v39
	v_exp_f32_e32 v40, v40
	v_exp_f32_e32 v41, v41
	v_exp_f32_e32 v42, v42
	v_exp_f32_e32 v43, v43
	v_exp_f32_e32 v44, v44
	v_exp_f32_e32 v45, v45
	v_exp_f32_e32 v46, v46
	v_exp_f32_e32 v47, v47
	v_exp_f32_e32 v48, v48
	v_exp_f32_e32 v49, v49
	v_pk_add_f32 v[138:139], v[34:35], v[36:37]
	v_pk_add_f32 v[140:141], v[38:39], v[40:41]
	v_pk_add_f32 v[142:143], v[42:43], v[44:45]
	v_pk_add_f32 v[144:145], v[46:47], v[48:49]
	v_pk_add_f32 v[138:139], v[138:139], v[140:141]
	v_pk_add_f32 v[142:143], v[142:143], v[144:145]
	v_pk_add_f32 v[138:139], v[138:139], v[142:143]
	v_add_f32_e32 v140, v138, v139
	v_add_f32_e32 v235, v235, v140
	v_cvt_pk_bf16_f32 v138, v34, v35
	v_cvt_pk_bf16_f32 v139, v36, v37
	v_cvt_pk_bf16_f32 v140, v38, v39
	v_cvt_pk_bf16_f32 v141, v40, v41
	v_cvt_pk_bf16_f32 v142, v42, v43
	v_cvt_pk_bf16_f32 v143, v44, v45
	v_cvt_pk_bf16_f32 v144, v46, v47
	v_cvt_pk_bf16_f32 v145, v48, v49
	s_waitcnt lgkmcnt(3)
	v_mfma_f32_16x16x32_bf16 v[18:21], v[50:53], v[138:141], v[18:21]
	s_waitcnt lgkmcnt(2)
	v_mfma_f32_16x16x32_bf16 v[18:21], v[54:57], v[142:145], v[18:21]
	ds_read_b128 v[50:53], v234 offset:13824
	ds_read_b128 v[54:57], v234 offset:13888
	s_waitcnt lgkmcnt(3)
	v_mfma_f32_16x16x32_bf16 v[22:25], v[58:61], v[138:141], v[22:25]
	s_waitcnt lgkmcnt(2)
	v_mfma_f32_16x16x32_bf16 v[22:25], v[62:65], v[142:145], v[22:25]
	ds_read_b128 v[58:61], v234 offset:16128
	ds_read_b128 v[62:65], v234 offset:16192
	s_waitcnt lgkmcnt(3)
	v_mfma_f32_16x16x32_bf16 v[26:29], v[50:53], v[138:141], v[26:29]
	s_waitcnt lgkmcnt(2)
	v_mfma_f32_16x16x32_bf16 v[26:29], v[54:57], v[142:145], v[26:29]
	s_waitcnt lgkmcnt(1)
	v_mfma_f32_16x16x32_bf16 v[30:33], v[58:61], v[138:141], v[30:33]
	s_waitcnt lgkmcnt(0)
	v_mfma_f32_16x16x32_bf16 v[30:33], v[62:65], v[142:145], v[30:33]
.Lsb16_end_0:
	s_add_i32 s20, s20, 1
	s_add_i32 s25, s25, 4
	s_cmp_eq_u32 s20, s101
	s_barrier
	s_cbranch_scc1 .LBB0_2180

.Lsb16_wr_1:
	ds_write_b128 v153, v[82:85]
	ds_write_b128 v153, v[86:89] offset:9216
	ds_write_b128 v155, v[90:93]
	ds_write_b128 v155, v[94:97] offset:9216
	s_add_i32 s22, s20, 3
	s_cmp_ge_u32 s22, s101
	s_cbranch_scc1 .Lsb16_nost_1
	v_mov_b32_e32 v34, s25
	ds_read_b32 v34, v34 offset:12
	s_waitcnt lgkmcnt(0)
	v_ashrrev_i32_e32 v35, 31, v34
	v_lshlrev_b64 v[34:35], 13, v[34:35]
	v_lshl_add_u64 v[36:37], v[134:135], 0, v[34:35]
	v_lshl_add_u64 v[34:35], v[136:137], 0, v[34:35]
	v_lshl_add_u64 v[38:39], v[36:37], 0, v[106:107]
	v_lshl_add_u64 v[36:37], v[36:37], 0, v[108:109]
	v_lshl_add_u64 v[40:41], v[34:35], 0, v[106:107]
	global_load_dwordx4 v[82:85], v[38:39], off
	global_load_dwordx4 v[86:89], v[40:41], off
	v_lshl_add_u64 v[34:35], v[34:35], 0, v[108:109]
	global_load_dwordx4 v[90:93], v[36:37], off
	global_load_dwordx4 v[94:97], v[34:35], off
.Lsb16_nost_1:
	v_mov_b32_e32 v34, s25
	ds_read_b32 v138, v34
	s_waitcnt lgkmcnt(0)
	v_readfirstlane_b32 s76, v138
	s_lshr_b32 s77, s76, 5
	s_lshl_b32 s77, s77, 2
	s_and_b32 s78, s76, 31
	v_add_u32_e32 v35, s77, v168
	v_add_u32_e32 v35, 0x11200, v35
	ds_read2_b32 v[36:37], v35 offset1:4
	ds_read2_b32 v[38:39], v35 offset0:8 offset1:12
	s_waitcnt lgkmcnt(0)
	v_or_b32_e32 v34, v36, v37
	v_or_b32_e32 v35, v38, v39
	s_nop 0
	v_readfirstlane_b32 s79, v34
	v_readfirstlane_b32 s80, v35
	s_bitcmp1_b32 s79, s78
	s_cselect_b32 s81, 1, 0
	s_bitcmp1_b32 s80, s78
	s_cselect_b32 s82, 1, 0
	s_or_b32 s83, s81, s82
	s_cmp_eq_u32 s83, 0
	s_cbranch_scc1 .Lsb16_end_1
	s_lshl_b32 s83, s76, 6
	v_subrev_u32_e32 v147, s83, v239
	v_cndmask_b32_e64 v146, v36, v37, s[86:87]
	v_cndmask_b32_e64 v151, v38, v39, s[86:87]
	v_lshrrev_b32_e32 v146, s78, v146
	v_lshrrev_b32_e32 v151, s78, v151
	v_and_b32_e32 v146, 1, v146
	v_and_b32_e32 v151, 1, v151
	v_cmp_ne_u32_e32 vcc, 0, v146
	s_cmp_eq_u32 s81, 0
	s_nop 0
	v_cndmask_b32_e32 v146, v213, v100, vcc
	s_cbranch_scc1 .Lsb16_g1_1
	ds_read_b128 v[50:53], v234 offset:18432
	ds_read_b128 v[54:57], v234 offset:18496
	ds_read_b128 v[58:61], v234 offset:20736
	ds_read_b128 v[62:65], v234 offset:20800
	s_waitcnt lgkmcnt(3)
	v_mfma_f32_16x16x32_bf16 v[34:37], v[50:53], v[66:69], 0
	s_waitcnt lgkmcnt(2)
	v_mfma_f32_16x16x32_bf16 v[34:37], v[54:57], v[70:73], v[34:37]
	ds_read_b128 v[50:53], v234 offset:23040
	ds_read_b128 v[54:57], v234 offset:23104
	s_waitcnt lgkmcnt(3)
	v_mfma_f32_16x16x32_bf16 v[38:41], v[58:61], v[66:69], 0
	s_waitcnt lgkmcnt(2)
	v_mfma_f32_16x16x32_bf16 v[38:41], v[62:65], v[70:73], v[38:41]
	ds_read_b128 v[58:61], v234 offset:25344
	ds_read_b128 v[62:65], v234 offset:25408
	s_waitcnt lgkmcnt(3)
	v_mfma_f32_16x16x32_bf16 v[42:45], v[50:53], v[66:69], 0
	s_waitcnt lgkmcnt(2)
	v_mfma_f32_16x16x32_bf16 v[42:45], v[54:57], v[70:73], v[42:45]
	s_waitcnt lgkmcnt(1)
	v_mfma_f32_16x16x32_bf16 v[46:49], v[58:61], v[66:69], 0
	s_waitcnt lgkmcnt(0)
	v_mfma_f32_16x16x32_bf16 v[46:49], v[62:65], v[70:73], v[46:49]
	ds_read_b128 v[50:53], v234 offset:27648
	ds_read_b128 v[54:57], v234 offset:27712
	ds_read_b128 v[58:61], v234 offset:29952
	ds_read_b128 v[62:65], v234 offset:30016
	v_pk_fma_f32 v[34:35], v[34:35], s[48:49], v[146:147] op_sel_hi:[1,0,0]
	v_pk_fma_f32 v[36:37], v[36:37], s[48:49], v[146:147] op_sel_hi:[1,0,0]
	v_pk_fma_f32 v[38:39], v[38:39], s[48:49], v[146:147] op_sel_hi:[1,0,0]
	v_pk_fma_f32 v[40:41], v[40:41], s[48:49], v[146:147] op_sel_hi:[1,0,0]
	v_pk_fma_f32 v[42:43], v[42:43], s[48:49], v[146:147] op_sel_hi:[1,0,0]
	v_pk_fma_f32 v[44:45], v[44:45], s[48:49], v[146:147] op_sel_hi:[1,0,0]
	v_pk_fma_f32 v[46:47], v[46:47], s[48:49], v[146:147] op_sel_hi:[1,0,0]
	v_pk_fma_f32 v[48:49], v[48:49], s[48:49], v[146:147] op_sel_hi:[1,0,0]
	s_cmp_lg_u32 s76, s72
	s_cbranch_scc1 .Lsb16_nm0_1
	v_cmp_le_i32_e64 s[98:99], 0, v147
	s_nop 1
	v_cndmask_b32_e64 v34, v213, v34, s[98:99]
	v_cmp_le_i32_e64 s[98:99], 1, v147
	s_nop 1
	v_cndmask_b32_e64 v35, v213, v35, s[98:99]
	v_cmp_le_i32_e64 s[98:99], 2, v147
	s_nop 1
	v_cndmask_b32_e64 v36, v213, v36, s[98:99]
	v_cmp_le_i32_e64 s[98:99], 3, v147
	s_nop 1
	v_cndmask_b32_e64 v37, v213, v37, s[98:99]
	v_cmp_le_i32_e64 s[98:99], 16, v147
	s_nop 1
	v_cndmask_b32_e64 v38, v213, v38, s[98:99]
	v_cmp_le_i32_e64 s[98:99], 17, v147
	s_nop 1
	v_cndmask_b32_e64 v39, v213, v39, s[98:99]
	v_cmp_le_i32_e64 s[98:99], 18, v147
	s_nop 1
	v_cndmask_b32_e64 v40, v213, v40, s[98:99]
	v_cmp_le_i32_e64 s[98:99], 19, v147
	s_nop 1
	v_cndmask_b32_e64 v41, v213, v41, s[98:99]
	v_cmp_le_i32_e64 s[98:99], 32, v147
	s_nop 1
	v_cndmask_b32_e64 v42, v213, v42, s[98:99]
	v_cmp_le_i32_e64 s[98:99], 33, v147
	s_nop 1
	v_cndmask_b32_e64 v43, v213, v43, s[98:99]
	v_cmp_le_i32_e64 s[98:99], 34, v147
	s_nop 1
	v_cndmask_b32_e64 v44, v213, v44, s[98:99]
	v_cmp_le_i32_e64 s[98:99], 35, v147
	s_nop 1
	v_cndmask_b32_e64 v45, v213, v45, s[98:99]
	v_cmp_le_i32_e64 s[98:99], 48, v147
	s_nop 1
	v_cndmask_b32_e64 v46, v213, v46, s[98:99]
	v_cmp_le_i32_e64 s[98:99], 49, v147
	s_nop 1
	v_cndmask_b32_e64 v47, v213, v47, s[98:99]
	v_cmp_le_i32_e64 s[98:99], 50, v147
	s_nop 1
	v_cndmask_b32_e64 v48, v213, v48, s[98:99]
	v_cmp_le_i32_e64 s[98:99], 51, v147
	s_nop 1
	v_cndmask_b32_e64 v49, v213, v49, s[98:99]
.Lsb16_nm0_1:
	v_exp_f32_e32 v34, v34
	v_exp_f32_e32 v35, v35
	v_exp_f32_e32 v36, v36
	v_exp_f32_e32 v37, v37
	v_exp_f32_e32 v38, v38
	v_exp_f32_e32 v39, v39
	v_exp_f32_e32 v40, v40
	v_exp_f32_e32 v41, v41
	v_exp_f32_e32 v42, v42
	v_exp_f32_e32 v43, v43
	v_exp_f32_e32 v44, v44
	v_exp_f32_e32 v45, v45
	v_exp_f32_e32 v46, v46
	v_exp_f32_e32 v47, v47
	v_exp_f32_e32 v48, v48
	v_exp_f32_e32 v49, v49
	v_pk_add_f32 v[138:139], v[34:35], v[36:37]
	v_pk_add_f32 v[140:141], v[38:39], v[40:41]
	v_pk_add_f32 v[142:143], v[42:43], v[44:45]
	v_pk_add_f32 v[144:145], v[46:47], v[48:49]
	v_pk_add_f32 v[138:139], v[138:139], v[140:141]
	v_pk_add_f32 v[142:143], v[142:143], v[144:145]
	v_pk_add_f32 v[138:139], v[138:139], v[142:143]
	v_add_f32_e32 v140, v138, v139
	v_add_f32_e32 v129, v129, v140
	v_cvt_pk_bf16_f32 v138, v34, v35
	v_cvt_pk_bf16_f32 v139, v36, v37
	v_cvt_pk_bf16_f32 v140, v38, v39
	v_cvt_pk_bf16_f32 v141, v40, v41
	v_cvt_pk_bf16_f32 v142, v42, v43
	v_cvt_pk_bf16_f32 v143, v44, v45
	v_cvt_pk_bf16_f32 v144, v46, v47
	v_cvt_pk_bf16_f32 v145, v48, v49
	s_waitcnt lgkmcnt(3)
	v_mfma_f32_16x16x32_bf16 v[2:5], v[50:53], v[138:141], v[2:5]
	s_waitcnt lgkmcnt(2)
	v_mfma_f32_16x16x32_bf16 v[2:5], v[54:57], v[142:145], v[2:5]
	ds_read_b128 v[50:53], v234 offset:32256
	ds_read_b128 v[54:57], v234 offset:32320
	s_waitcnt lgkmcnt(3)
	v_mfma_f32_16x16x32_bf16 v[6:9], v[58:61], v[138:141], v[6:9]
	s_waitcnt lgkmcnt(2)
	v_mfma_f32_16x16x32_bf16 v[6:9], v[62:65], v[142:145], v[6:9]
	ds_read_b128 v[58:61], v234 offset:34560
	ds_read_b128 v[62:65], v234 offset:34624
	s_waitcnt lgkmcnt(3)
	v_mfma_f32_16x16x32_bf16 v[10:13], v[50:53], v[138:141], v[10:13]
	s_waitcnt lgkmcnt(2)
	v_mfma_f32_16x16x32_bf16 v[10:13], v[54:57], v[142:145], v[10:13]
	s_waitcnt lgkmcnt(1)
	v_mfma_f32_16x16x32_bf16 v[14:17], v[58:61], v[138:141], v[14:17]
	s_waitcnt lgkmcnt(0)
	v_mfma_f32_16x16x32_bf16 v[14:17], v[62:65], v[142:145], v[14:17]
.Lsb16_g1_1:
	s_cmp_eq_u32 s82, 0
	s_cbranch_scc1 .Lsb16_end_1
	v_cmp_ne_u32_e32 vcc, 0, v151
	v_add_u32_e32 v147, 2, v147
	ds_read_b128 v[50:53], v234 offset:18432
	ds_read_b128 v[54:57], v234 offset:18496
	ds_read_b128 v[58:61], v234 offset:20736
	ds_read_b128 v[62:65], v234 offset:20800
	v_cndmask_b32_e32 v146, v213, v100, vcc
	s_waitcnt lgkmcnt(3)
	v_mfma_f32_16x16x32_bf16 v[34:37], v[50:53], v[74:77], 0
	s_waitcnt lgkmcnt(2)
	v_mfma_f32_16x16x32_bf16 v[34:37], v[54:57], v[78:81], v[34:37]
	ds_read_b128 v[50:53], v234 offset:23040
	ds_read_b128 v[54:57], v234 offset:23104
	s_waitcnt lgkmcnt(3)
	v_mfma_f32_16x16x32_bf16 v[38:41], v[58:61], v[74:77], 0
	s_waitcnt lgkmcnt(2)
	v_mfma_f32_16x16x32_bf16 v[38:41], v[62:65], v[78:81], v[38:41]
	ds_read_b128 v[58:61], v234 offset:25344
	ds_read_b128 v[62:65], v234 offset:25408
	s_waitcnt lgkmcnt(3)
	v_mfma_f32_16x16x32_bf16 v[42:45], v[50:53], v[74:77], 0
	s_waitcnt lgkmcnt(2)
	v_mfma_f32_16x16x32_bf16 v[42:45], v[54:57], v[78:81], v[42:45]
	s_waitcnt lgkmcnt(1)
	v_mfma_f32_16x16x32_bf16 v[46:49], v[58:61], v[74:77], 0
	s_waitcnt lgkmcnt(0)
	v_mfma_f32_16x16x32_bf16 v[46:49], v[62:65], v[78:81], v[46:49]
	ds_read_b128 v[50:53], v234 offset:27648
	ds_read_b128 v[54:57], v234 offset:27712
	ds_read_b128 v[58:61], v234 offset:29952
	ds_read_b128 v[62:65], v234 offset:30016
	v_pk_fma_f32 v[34:35], v[34:35], s[48:49], v[146:147] op_sel_hi:[1,0,0]
	v_pk_fma_f32 v[36:37], v[36:37], s[48:49], v[146:147] op_sel_hi:[1,0,0]
	v_pk_fma_f32 v[38:39], v[38:39], s[48:49], v[146:147] op_sel_hi:[1,0,0]
	v_pk_fma_f32 v[40:41], v[40:41], s[48:49], v[146:147] op_sel_hi:[1,0,0]
	v_pk_fma_f32 v[42:43], v[42:43], s[48:49], v[146:147] op_sel_hi:[1,0,0]
	v_pk_fma_f32 v[44:45], v[44:45], s[48:49], v[146:147] op_sel_hi:[1,0,0]
	v_pk_fma_f32 v[46:47], v[46:47], s[48:49], v[146:147] op_sel_hi:[1,0,0]
	v_pk_fma_f32 v[48:49], v[48:49], s[48:49], v[146:147] op_sel_hi:[1,0,0]
	s_cmp_lg_u32 s76, s72
	s_cbranch_scc1 .Lsb16_nm1_1
	v_cmp_le_i32_e64 s[98:99], 0, v147
	s_nop 1
	v_cndmask_b32_e64 v34, v213, v34, s[98:99]
	v_cmp_le_i32_e64 s[98:99], 1, v147
	s_nop 1
	v_cndmask_b32_e64 v35, v213, v35, s[98:99]
	v_cmp_le_i32_e64 s[98:99], 2, v147
	s_nop 1
	v_cndmask_b32_e64 v36, v213, v36, s[98:99]
	v_cmp_le_i32_e64 s[98:99], 3, v147
	s_nop 1
	v_cndmask_b32_e64 v37, v213, v37, s[98:99]
	v_cmp_le_i32_e64 s[98:99], 16, v147
	s_nop 1
	v_cndmask_b32_e64 v38, v213, v38, s[98:99]
	v_cmp_le_i32_e64 s[98:99], 17, v147
	s_nop 1
	v_cndmask_b32_e64 v39, v213, v39, s[98:99]
	v_cmp_le_i32_e64 s[98:99], 18, v147
	s_nop 1
	v_cndmask_b32_e64 v40, v213, v40, s[98:99]
	v_cmp_le_i32_e64 s[98:99], 19, v147
	s_nop 1
	v_cndmask_b32_e64 v41, v213, v41, s[98:99]
	v_cmp_le_i32_e64 s[98:99], 32, v147
	s_nop 1
	v_cndmask_b32_e64 v42, v213, v42, s[98:99]
	v_cmp_le_i32_e64 s[98:99], 33, v147
	s_nop 1
	v_cndmask_b32_e64 v43, v213, v43, s[98:99]
	v_cmp_le_i32_e64 s[98:99], 34, v147
	s_nop 1
	v_cndmask_b32_e64 v44, v213, v44, s[98:99]
	v_cmp_le_i32_e64 s[98:99], 35, v147
	s_nop 1
	v_cndmask_b32_e64 v45, v213, v45, s[98:99]
	v_cmp_le_i32_e64 s[98:99], 48, v147
	s_nop 1
	v_cndmask_b32_e64 v46, v213, v46, s[98:99]
	v_cmp_le_i32_e64 s[98:99], 49, v147
	s_nop 1
	v_cndmask_b32_e64 v47, v213, v47, s[98:99]
	v_cmp_le_i32_e64 s[98:99], 50, v147
	s_nop 1
	v_cndmask_b32_e64 v48, v213, v48, s[98:99]
	v_cmp_le_i32_e64 s[98:99], 51, v147
	s_nop 1
	v_cndmask_b32_e64 v49, v213, v49, s[98:99]
.Lsb16_nm1_1:
	v_exp_f32_e32 v34, v34
	v_exp_f32_e32 v35, v35
	v_exp_f32_e32 v36, v36
	v_exp_f32_e32 v37, v37
	v_exp_f32_e32 v38, v38
	v_exp_f32_e32 v39, v39
	v_exp_f32_e32 v40, v40
	v_exp_f32_e32 v41, v41
	v_exp_f32_e32 v42, v42
	v_exp_f32_e32 v43, v43
	v_exp_f32_e32 v44, v44
	v_exp_f32_e32 v45, v45
	v_exp_f32_e32 v46, v46
	v_exp_f32_e32 v47, v47
	v_exp_f32_e32 v48, v48
	v_exp_f32_e32 v49, v49
	v_pk_add_f32 v[138:139], v[34:35], v[36:37]
	v_pk_add_f32 v[140:141], v[38:39], v[40:41]
	v_pk_add_f32 v[142:143], v[42:43], v[44:45]
	v_pk_add_f32 v[144:145], v[46:47], v[48:49]
	v_pk_add_f32 v[138:139], v[138:139], v[140:141]
	v_pk_add_f32 v[142:143], v[142:143], v[144:145]
	v_pk_add_f32 v[138:139], v[138:139], v[142:143]
	v_add_f32_e32 v140, v138, v139
	v_add_f32_e32 v235, v235, v140
	v_cvt_pk_bf16_f32 v138, v34, v35
	v_cvt_pk_bf16_f32 v139, v36, v37
	v_cvt_pk_bf16_f32 v140, v38, v39
	v_cvt_pk_bf16_f32 v141, v40, v41
	v_cvt_pk_bf16_f32 v142, v42, v43
	v_cvt_pk_bf16_f32 v143, v44, v45
	v_cvt_pk_bf16_f32 v144, v46, v47
	v_cvt_pk_bf16_f32 v145, v48, v49
	s_waitcnt lgkmcnt(3)
	v_mfma_f32_16x16x32_bf16 v[18:21], v[50:53], v[138:141], v[18:21]
	s_waitcnt lgkmcnt(2)
	v_mfma_f32_16x16x32_bf16 v[18:21], v[54:57], v[142:145], v[18:21]
	ds_read_b128 v[50:53], v234 offset:32256
	ds_read_b128 v[54:57], v234 offset:32320
	s_waitcnt lgkmcnt(3)
	v_mfma_f32_16x16x32_bf16 v[22:25], v[58:61], v[138:141], v[22:25]
	s_waitcnt lgkmcnt(2)
	v_mfma_f32_16x16x32_bf16 v[22:25], v[62:65], v[142:145], v[22:25]
	ds_read_b128 v[58:61], v234 offset:34560
	ds_read_b128 v[62:65], v234 offset:34624
	s_waitcnt lgkmcnt(3)
	v_mfma_f32_16x16x32_bf16 v[26:29], v[50:53], v[138:141], v[26:29]
	s_waitcnt lgkmcnt(2)
	v_mfma_f32_16x16x32_bf16 v[26:29], v[54:57], v[142:145], v[26:29]
	s_waitcnt lgkmcnt(1)
	v_mfma_f32_16x16x32_bf16 v[30:33], v[58:61], v[138:141], v[30:33]
	s_waitcnt lgkmcnt(0)
	v_mfma_f32_16x16x32_bf16 v[30:33], v[62:65], v[142:145], v[30:33]
.Lsb16_end_1:
	s_add_i32 s20, s20, 1
	s_add_i32 s25, s25, 4
	s_cmp_eq_u32 s20, s101
	s_barrier
	s_cbranch_scc1 .LBB0_2180
	s_branch .Lsb16_step_0

	.amdhsa_kernel _Z15yoco_megakernel5KArgsii
		.amdhsa_group_segment_fixed_size 73744
		.amdhsa_private_segment_fixed_size 0
		.amdhsa_kernarg_size 512
		.amdhsa_user_sgpr_count 2
		.amdhsa_user_sgpr_dispatch_ptr 0
		.amdhsa_user_sgpr_queue_ptr 0
		.amdhsa_user_sgpr_kernarg_segment_ptr 1
		.amdhsa_user_sgpr_dispatch_id 0
		.amdhsa_user_sgpr_kernarg_preload_length 0
		.amdhsa_user_sgpr_kernarg_preload_offset 0
		.amdhsa_user_sgpr_private_segment_size 0
		.amdhsa_uses_dynamic_stack 0
		.amdhsa_enable_private_segment 0
		.amdhsa_system_sgpr_workgroup_id_x 1
		.amdhsa_system_sgpr_workgroup_id_y 0
		.amdhsa_system_sgpr_workgroup_id_z 0
		.amdhsa_system_sgpr_workgroup_info 0
		.amdhsa_system_vgpr_workitem_id 2
		.amdhsa_next_free_vgpr 256
		.amdhsa_next_free_sgpr 102
		.amdhsa_accum_offset 256
		.amdhsa_reserve_vcc 1
		.amdhsa_float_round_mode_32 0
		.amdhsa_float_round_mode_16_64 0
		.amdhsa_float_denorm_mode_32 3
		.amdhsa_float_denorm_mode_16_64 3
		.amdhsa_dx10_clamp 1
		.amdhsa_ieee_mode 1
		.amdhsa_fp16_overflow 0
		.amdhsa_tg_split 0
		.amdhsa_exception_fp_ieee_invalid_op 0
		.amdhsa_exception_fp_denorm_src 0
		.amdhsa_exception_fp_ieee_div_zero 0
		.amdhsa_exception_fp_ieee_overflow 0
		.amdhsa_exception_fp_ieee_underflow 0
		.amdhsa_exception_fp_ieee_inexact 0
		.amdhsa_exception_int_div_zero 0
	.end_amdhsa_kernel

amdhsa.kernels:
  - .agpr_count:     0
    .args:
      - .offset:         0
        .size:           248
        .value_kind:     by_value
      - .offset:         248
        .size:           4
        .value_kind:     by_value
      - .offset:         252
        .size:           4
        .value_kind:     by_value
      - .offset:         256
        .size:           4
        .value_kind:     hidden_block_count_x
      - .offset:         260
        .size:           4
        .value_kind:     hidden_block_count_y
      - .offset:         264
        .size:           4
        .value_kind:     hidden_block_count_z
      - .offset:         268
        .size:           2
        .value_kind:     hidden_group_size_x
      - .offset:         270
        .size:           2
        .value_kind:     hidden_group_size_y
      - .offset:         272
        .size:           2
        .value_kind:     hidden_group_size_z
      - .offset:         274
        .size:           2
        .value_kind:     hidden_remainder_x
      - .offset:         276
        .size:           2
        .value_kind:     hidden_remainder_y
      - .offset:         278
        .size:           2
        .value_kind:     hidden_remainder_z
      - .offset:         296
        .size:           8
        .value_kind:     hidden_global_offset_x
      - .offset:         304
        .size:           8
        .value_kind:     hidden_global_offset_y
      - .offset:         312
        .size:           8
        .value_kind:     hidden_global_offset_z
      - .offset:         320
        .size:           2
        .value_kind:     hidden_grid_dims
      - .offset:         344
        .size:           8
        .value_kind:     hidden_multigrid_sync_arg
    .group_segment_fixed_size: 73744
    .kernarg_segment_align: 8
    .kernarg_segment_size: 512
    .language:       OpenCL C
    .language_version:
      - 2
      - 0
    .max_flat_workgroup_size: 256
    .name:           _Z15yoco_megakernel5KArgsii
    .private_segment_fixed_size: 0
    .sgpr_count:     108
    .sgpr_spill_count: 38
    .symbol:         _Z15yoco_megakernel5KArgsii.kd
    .uniform_work_group_size: 1
    .uses_dynamic_stack: false
    .vgpr_count:     256
    .vgpr_spill_count: 0
    .wavefront_size: 64
